# attention: balanced head-to-workgroup assignment (steep and flat ALiBi heads mixed per workgroup) on top of reverse order + exact zero-probability skip
# speedup vs baseline: 1.0341x; 1.0039x over previous
; __device__ __forceinline__ float fexp2(float x) { return __builtin_amdgcn_exp2f(x); }
; __device__ __forceinline__ void attn_unit(const PT& p, LAS unsigned char* lds, int tid, int lane, int wave, int b, int hd, int qb, float lam) {
;     ...
;     const int qw0 = qb * 128 + 32 * wq, q = qw0 + r32; const unsigned tokq = (unsigned)(b * SEQ + q), tokb = (unsigned)(b * SEQ);
;     const float slope2 = fexp2(-0.5f * (float)(hd + 1)) * LOG2E;
; __device__ __forceinline__ void phase_attn(const PT& p, LAS unsigned char* lds, int tid, int lane, int wave) {
;     ...
;     for (int u = blockIdx.x; u < NBATCH * 16 * 8; u += gridDim.x) {
;         const int j = u & 7, hd = (u >> 3) & 15, b = u >> 7;
; #pragma unroll 1
;         for (int k = 0; k < 2; ++k) attn_unit(p, lds, tid, lane, wave, b, hd, k == 0 ? 15 - j : j, lam);
.LBB0_1072:
	s_and_b32 s98, s90, 0xffffffc0
	s_bfe_u32 s99, s90, 0x30003
	s_or_b32 s98, s98, s99
	s_and_b32 s99, s90, 7
	s_lshl_b32 s99, s99, 3
	s_or_b32 s98, s98, s99
	s_lshr_b32 s99, s90, 8
	s_and_b32 s36, s99, 1
	s_mul_i32 s36, s36, 7
	s_lshr_b32 s99, s99, 1
	s_lshl_b32 s99, s99, 3
	s_or_b32 s99, s99, s36
	s_lshl_b32 s36, s98, 15
	s_bfe_u32 s37, s98, 0x40003
	s_xor_b32 s37, s37, s99
	s_and_b32 s36, s36, 0xffc00000
	s_lshl_b32 s91, s37, 7
	s_or_b32 s36, s91, s36
	s_add_i32 s37, s37, 1
	v_add_u32_e32 v235, s36, v229
	v_add_u32_e32 v236, s36, v230
	v_add_u32_e32 v237, s36, v231
	v_add_u32_e32 v238, s36, v232
	s_lshl_b32 s36, s98, 4
	v_cvt_f32_ubyte0_e32 v0, s37
	s_and_b32 s94, s36, 0xfffff800
	v_mul_f32_e32 v0, -0.5, v0
	v_exp_f32_e32 v2, v0
	v_or_b32_e32 v3, s91, v201
	v_add_u32_e32 v0, s94, v202
	v_lshl_or_b32 v50, v0, 11, v3
	v_lshlrev_b64 v[0:1], 1, v[50:51]
	v_lshl_add_u64 v[180:181], s[46:47], 0, v[0:1]
	v_lshl_add_u64 v[182:183], s[42:43], 0, v[0:1]
	v_add_u32_e32 v0, s94, v203
	v_lshl_or_b32 v50, v0, 11, v3
	v_lshlrev_b64 v[0:1], 1, v[50:51]
	v_lshl_add_u64 v[184:185], s[46:47], 0, v[0:1]
	v_lshl_add_u64 v[186:187], s[42:43], 0, v[0:1]
	v_add_u32_e32 v0, s94, v204
	v_lshl_or_b32 v50, v0, 11, v3
	v_lshlrev_b64 v[0:1], 1, v[50:51]
	v_lshl_add_u64 v[188:189], s[46:47], 0, v[0:1]
	v_lshl_add_u64 v[190:191], s[42:43], 0, v[0:1]
	v_add_u32_e32 v0, s94, v205
	v_lshl_or_b32 v50, v0, 11, v3
	s_and_b32 s92, s98, 7
	v_lshlrev_b64 v[0:1], 1, v[50:51]
	s_xor_b32 s93, s92, 15
	v_add_u32_e32 v239, s91, v200
	v_lshl_add_u64 v[192:193], s[46:47], 0, v[0:1]
	v_lshl_add_u64 v[194:195], s[42:43], 0, v[0:1]
	v_mul_f32_e32 v240, 0x3fb8aa3b, v2
	s_mov_b64 s[36:37], -1
	v_writelane_b32 v249, s38, 37
	s_branch .LBB0_1074
